# phase 0 norm_rows<1>: kernel-argument pointer s_loads hoisted out of the row loop, next row's 4 KB prefetched into spare VGPRs while the current row is reduced/converted/stored; on top of v049
# baseline (speedup 1.0000x reference)
.Lcw_done:
.LBB0_254:
	s_cmp_gt_i32 s14, 0x800f
	s_cbranch_scc1 .LBB0_273
	v_mbcnt_lo_u32_b32 v1, -1, 0
	v_mbcnt_hi_u32_b32 v3, -1, v1
	v_and_b32_e32 v1, 64, v3
	v_add_u32_e32 v4, 64, v1
	v_xor_b32_e32 v1, 1, v3
	v_cmp_lt_i32_e32 vcc, v1, v4
	v_xor_b32_e32 v5, 2, v3
	s_load_dwordx2 s[16:17], s[10:11], 0xd8
	v_cndmask_b32_e32 v1, v3, v1, vcc
	v_cmp_lt_i32_e32 vcc, v5, v4
	s_add_u32 s20, s12, 0x80000
	v_mov_b32_e32 v19, 0
	v_cndmask_b32_e32 v5, v3, v5, vcc
	v_lshlrev_b32_e32 v30, 2, v5
	v_xor_b32_e32 v5, 4, v3
	v_cmp_lt_i32_e32 vcc, v5, v4
	v_lshlrev_b32_e32 v18, 3, v2
	s_addc_u32 s21, s13, 0
	v_cndmask_b32_e32 v5, v3, v5, vcc
	v_lshlrev_b32_e32 v31, 2, v5
	v_xor_b32_e32 v5, 8, v3
	v_cmp_lt_i32_e32 vcc, v5, v4
	s_lshl_b32 s6, s30, 9
	s_lshl_b32 s7, s15, 6
	v_cndmask_b32_e32 v5, v3, v5, vcc
	v_lshlrev_b32_e32 v32, 2, v5
	v_xor_b32_e32 v5, 16, v3
	v_cmp_lt_i32_e32 vcc, v5, v4
	s_mov_b64 s[4:5], 0x6700000
	s_add_i32 s6, s6, s7
	v_cndmask_b32_e32 v5, v3, v5, vcc
	v_lshlrev_b32_e32 v33, 2, v5
	v_xor_b32_e32 v5, 32, v3
	v_cmp_lt_i32_e32 vcc, v5, v4
	s_ashr_i32 s15, s14, 31
	s_ashr_i32 s77, s76, 31
	v_cndmask_b32_e32 v3, v3, v5, vcc
	v_lshl_add_u64 v[4:5], s[12:13], 0, v[18:19]
	v_lshlrev_b32_e32 v18, 2, v2
	v_lshlrev_b32_e32 v34, 2, v3
	v_lshl_add_u64 v[20:21], v[4:5], 0, s[4:5]
	v_lshl_add_u64 v[4:5], s[12:13], 0, v[18:19]
	s_mov_b64 s[4:5], 0x1ca40000
	v_or_b32_e32 v3, s6, v2
	s_mov_b32 s19, 0
	v_lshlrev_b32_e32 v1, 2, v1
	v_cmp_gt_u32_e64 s[8:9], 4, v2
	v_lshl_add_u64 v[22:23], v[4:5], 0, s[4:5]
	v_cmp_eq_u32_e64 s[4:5], 0, v2
	v_add_u32_e32 v18, 0xffe00000, v3
	s_lshl_b32 s30, s80, 9
	s_lshl_b64 s[22:23], s[14:15], 12
	s_lshl_b64 s[24:25], s[76:77], 12
	s_movk_i32 s31, 0x7fff
	v_lshlrev_b32_e32 v24, 4, v2
	v_mov_b32_e32 v25, v19
	s_mov_b32 s33, 0xffff0000
	s_load_dwordx2 s[36:37], s[10:11], 0x0
	s_load_dwordx2 s[38:39], s[10:11], 0x8
	s_waitcnt lgkmcnt(0)
	s_add_u32 s40, s36, s22
	s_addc_u32 s41, s37, s23
	s_add_i32 s42, s14, 0xffff8000
	s_ashr_i32 s43, s42, 31
	s_lshl_b64 s[42:43], s[42:43], 12
	s_add_u32 s42, s38, s42
	s_addc_u32 s43, s39, s43
	s_cmp_lt_i32 s14, 0x8000
	s_cselect_b32 s40, s40, s42
	s_cselect_b32 s41, s41, s43
	s_nop 0
	global_load_dwordx4 v[40:43], v24, s[40:41]
	global_load_dwordx4 v[44:47], v24, s[40:41] offset:1024
	global_load_dwordx4 v[48:51], v24, s[40:41] offset:2048
	global_load_dwordx4 v[52:55], v24, s[40:41] offset:3072
	s_waitcnt vmcnt(0)
	s_branch .LBB0_257

.LBB0_257:
	s_cmp_lt_i32 s14, 0x8000
	s_cselect_b64 s[6:7], -1, 0
	s_add_i32 s18, s14, 0xffff8000
	s_cmpk_gt_i32 s14, 0x7fff
	s_mov_b64 s[34:35], -1
	s_cbranch_scc0 .LBB0_259
	s_mov_b64 s[28:29], s[38:39]
	s_lshl_b64 s[34:35], s[18:19], 12
	s_mov_b32 s26, s14
	s_mov_b32 s27, s19
	s_add_u32 s28, s28, s34
	s_addc_u32 s29, s29, s35
	s_mov_b64 s[34:35], 0
.LBB0_259:
	s_andn2_b64 vcc, exec, s[34:35]
	s_cbranch_vccnz .LBB0_261
	s_mov_b64 s[26:27], s[36:37]
	s_add_u32 s28, s26, s22
	s_addc_u32 s29, s27, s23
	s_mov_b64 s[26:27], s[14:15]
.LBB0_261:
	s_waitcnt vmcnt(4)
	v_mov_b64_e32 v[14:15], v[40:41]
	v_mov_b64_e32 v[16:17], v[42:43]
	v_mov_b64_e32 v[10:11], v[44:45]
	v_mov_b64_e32 v[12:13], v[46:47]
	v_mov_b64_e32 v[6:7], v[48:49]
	v_mov_b64_e32 v[8:9], v[50:51]
	v_mov_b64_e32 v[2:3], v[52:53]
	v_mov_b64_e32 v[4:5], v[54:55]
	s_add_i32 s44, s14, s76
	s_cmp_lt_i32 s44, 0x8010
	s_cbranch_scc0 .Lnp_skip
	s_add_u32 s46, s22, s24
	s_addc_u32 s47, s23, s25
	s_add_u32 s40, s36, s46
	s_addc_u32 s41, s37, s47
	s_add_i32 s42, s44, 0xffff8000
	s_ashr_i32 s43, s42, 31
	s_lshl_b64 s[42:43], s[42:43], 12
	s_add_u32 s42, s38, s42
	s_addc_u32 s43, s39, s43
	s_cmp_lt_i32 s44, 0x8000
	s_cselect_b32 s40, s40, s42
	s_cselect_b32 s41, s41, s43
	s_nop 0
	global_load_dwordx4 v[40:43], v24, s[40:41]
	global_load_dwordx4 v[44:47], v24, s[40:41] offset:1024
	global_load_dwordx4 v[48:51], v24, s[40:41] offset:2048
	global_load_dwordx4 v[52:55], v24, s[40:41] offset:3072
.Lnp_skip:
	s_and_b64 s[6:7], s[6:7], exec
	s_cselect_b32 s7, s15, 0
	s_cselect_b32 s6, s14, s18
	s_waitcnt lgkmcnt(0)
	s_cselect_b32 s18, s17, s13
	s_cselect_b32 s28, s16, s12
	s_lshl_b64 s[6:7], s[6:7], 12
	s_add_u32 s6, s28, s6
	s_addc_u32 s7, s18, s7
	s_cmpk_gt_i32 s14, 0x7fff
	s_cselect_b64 s[28:29], -1, 0
	s_cmp_lt_i32 s14, 0x8000
	v_mul_f32_e32 v26, v15, v15
	v_mul_f32_e32 v27, v17, v17
	v_mul_f32_e32 v28, v11, v11
	v_mul_f32_e32 v29, v13, v13
	v_mul_f32_e32 v35, v7, v7
	v_mul_f32_e32 v36, v9, v9
	v_fmac_f32_e32 v26, v14, v14
	v_fmac_f32_e32 v27, v16, v16
	v_fmac_f32_e32 v28, v10, v10
	v_fmac_f32_e32 v29, v12, v12
	v_mul_f32_e32 v37, v3, v3
	v_mul_f32_e32 v38, v5, v5
	v_fmac_f32_e32 v35, v6, v6
	v_fmac_f32_e32 v36, v8, v8
	v_add_f32_e32 v26, v26, v27
	v_add_f32_e32 v27, v28, v29
	v_fmac_f32_e32 v37, v2, v2
	v_fmac_f32_e32 v38, v4, v4
	v_add_f32_e32 v28, v35, v36
	v_add_f32_e32 v26, v26, v27
	v_add_f32_e32 v26, v26, v28
	v_add_f32_e32 v27, v37, v38
	v_add_f32_e32 v26, v26, v27
	ds_bpermute_b32 v27, v1, v26
	v_lshl_add_u64 v[28:29], s[6:7], 0, v[24:25]
	s_waitcnt lgkmcnt(0)
	v_add_f32_e32 v26, v26, v27
	ds_bpermute_b32 v27, v30, v26
	s_waitcnt lgkmcnt(0)
	v_add_f32_e32 v26, v26, v27
	ds_bpermute_b32 v27, v31, v26
	s_waitcnt lgkmcnt(0)
	v_add_f32_e32 v26, v26, v27
	ds_bpermute_b32 v27, v32, v26
	s_waitcnt lgkmcnt(0)
	v_add_f32_e32 v26, v26, v27
	ds_bpermute_b32 v27, v33, v26
	s_waitcnt lgkmcnt(0)
	v_add_f32_e32 v35, v26, v27
	ds_bpermute_b32 v36, v34, v35
	s_cbranch_scc1 .LBB0_263
	global_store_dwordx4 v[28:29], v[14:17], off
